# GEMM prologues: accumulator zero-init moved up under the first vmcnt(4) load wait
# baseline (speedup 1.0000x reference)
; #define STAGEA(P, BASE, kt) do { const size_t SS_ = ssA; STAGE(P, BASE, kt); } while (0)
; #define STAGEB(P, BASE, kt) do { const size_t SS_ = ssB; STAGE(P, BASE, kt); } while (0)
; template <int EPI>
; __device__ void gemm8(const bf16* A, const bf16* Bt, const int K, const int ntN, const int ntTot, const EpiArgs ea, char* smem) {
;     ...
;     f32x4 acc[2][2][4][2];
; #pragma unroll
;     for (int a = 0; a < 2; ++a)
; #pragma unroll
;       for (int b = 0; b < 2; ++b)
; #pragma unroll
;         for (int m = 0; m < 4; ++m)
; #pragma unroll
;           for (int n = 0; n < 2; ++n) acc[a][b][m][n] = f32x4{0.f, 0.f, 0.f, 0.f};
;     s16x8 At[4][2], B0[2][2], B1[2][2];
;     __syncthreads();
;     if (EPI != EPI_RES) {
;       if (tid < 256) {
;         const float* sq = ea.ssq + (size_t)(brow + tid) * 8;
;         const f32x4 q0 = *(const f32x4*)sq, q1 = *(const f32x4*)(sq + 4);
;         ssl[tid] = rsqrtf((((q0[0] + q0[1]) + (q0[2] + q0[3])) + ((q1[0] + q1[1]) + (q1[2] + q1[3]))) * (1.f / 1024.f) + EPS);
;       }
;     }
;     STAGEB(SB(0, 0), B0g, 0); STAGEA(SA(0, 0), A0, 0);
;     STAGEB(SB(0, 1), B1g, 0); STAGEA(SA(0, 1), A1, 0);
.LBB0_171:
	s_mul_hi_i32 s0, s34, 0x2aaaaaab
	s_lshr_b32 s1, s0, 31
	s_ashr_i32 s2, s0, 1
	s_add_i32 s2, s2, s1
	s_lshl_b32 s42, s2, 8
	s_barrier
	s_mul_i32 s2, s2, 12
	s_sub_i32 s10, s34, s2
	s_ashr_i32 s43, s42, 31
	s_lshl_b32 s2, s10, 8
	s_lshl_b64 s[0:1], s[42:43], 7
	s_add_u32 s16, s18, s0
	s_addc_u32 s17, s19, s1
	s_ashr_i32 s3, s2, 31
	s_lshl_b64 s[2:3], s[2:3], 7
	s_add_u32 s4, s13, s2
	s_addc_u32 s5, s20, s3
	s_add_i32 s11, s23, 0x10000
	v_lshl_add_u64 v[2:3], s[4:5], 0, v[146:147]
	s_mov_b32 m0, s11
	s_mov_b64 s[2:3], 0x2000
	s_add_i32 s35, s23, 0x12000
	global_load_lds_dwordx4 v[2:3], off
	v_lshl_add_u64 v[4:5], v[2:3], 0, s[2:3]
	s_mov_b32 m0, s35
	v_lshl_add_u64 v[130:131], s[16:17], 0, v[146:147]
	global_load_lds_dwordx4 v[4:5], off
	s_mov_b32 m0, s23
	s_add_i32 s40, s23, 0x2000
	global_load_lds_dwordx4 v[130:131], off
	v_lshl_add_u64 v[4:5], v[130:131], 0, s[2:3]
	s_mov_b32 m0, s40
	s_mov_b64 s[2:3], 0x4000
	s_add_i32 s41, s23, 0x14000
	global_load_lds_dwordx4 v[4:5], off
	v_lshl_add_u64 v[4:5], v[2:3], 0, s[2:3]
	s_mov_b32 m0, s41
	s_mov_b64 s[16:17], 0x6000
	s_add_i32 s43, s23, 0x16000
	global_load_lds_dwordx4 v[4:5], off
	v_lshl_add_u64 v[4:5], v[2:3], 0, s[16:17]
	s_mov_b32 m0, s43
	s_add_i32 s44, s23, 0x4000
	global_load_lds_dwordx4 v[4:5], off
	v_lshl_add_u64 v[4:5], v[130:131], 0, s[2:3]
	s_mov_b32 m0, s44
	s_add_i32 s45, s23, 0x6000
	global_load_lds_dwordx4 v[4:5], off
	v_lshl_add_u64 v[4:5], v[130:131], 0, s[16:17]
	s_mov_b32 m0, s45
	s_nop 0
	global_load_lds_dwordx4 v[4:5], off
	v_mov_b32_e32 v6, 0
	v_mov_b32_e32 v7, 0
	v_mov_b32_e32 v8, 0
	v_mov_b32_e32 v9, 0
	v_mov_b32_e32 v10, 0
	v_mov_b32_e32 v11, 0
	v_mov_b32_e32 v22, 0
	v_mov_b32_e32 v23, 0
	v_mov_b32_e32 v24, 0
	v_mov_b32_e32 v25, 0
	v_mov_b32_e32 v26, 0
	v_mov_b32_e32 v27, 0
	v_mov_b32_e32 v28, 0
	v_mov_b32_e32 v29, 0
	v_mov_b32_e32 v30, 0
	v_mov_b32_e32 v31, 0
	v_mov_b32_e32 v32, 0
	v_mov_b32_e32 v33, 0
	v_mov_b32_e32 v54, 0
	v_mov_b32_e32 v55, 0
	v_mov_b32_e32 v56, 0
	v_mov_b32_e32 v57, 0
	v_mov_b32_e32 v74, 0
	v_mov_b32_e32 v75, 0
	v_mov_b32_e32 v76, 0
	v_mov_b32_e32 v77, 0
	v_mov_b32_e32 v90, 0
	v_mov_b32_e32 v91, 0
	v_mov_b32_e32 v92, 0
	v_mov_b32_e32 v93, 0
	v_mov_b32_e32 v106, 0
	v_mov_b32_e32 v107, 0
	v_mov_b32_e32 v108, 0
	v_mov_b32_e32 v109, 0
	v_mov_b32_e32 v114, 0
	v_mov_b32_e32 v115, 0
	v_mov_b32_e32 v116, 0
	v_mov_b32_e32 v117, 0
	v_mov_b32_e32 v118, 0
	v_mov_b32_e32 v119, 0
	v_mov_b32_e32 v120, 0
	v_mov_b32_e32 v121, 0
	v_mov_b32_e32 v122, 0
	v_mov_b32_e32 v123, 0
	v_mov_b32_e32 v124, 0
	v_mov_b32_e32 v125, 0
	v_mov_b32_e32 v126, 0
	v_mov_b32_e32 v127, 0
	v_mov_b32_e32 v128, 0
	v_mov_b32_e32 v129, 0
	v_mov_b32_e32 v34, 0
	v_mov_b32_e32 v35, 0
	v_mov_b32_e32 v36, 0
	v_mov_b32_e32 v37, 0
	v_mov_b32_e32 v38, 0
	v_mov_b32_e32 v39, 0
	v_mov_b32_e32 v40, 0
	v_mov_b32_e32 v41, 0
	v_mov_b32_e32 v42, 0
	v_mov_b32_e32 v43, 0
	v_mov_b32_e32 v44, 0
	v_mov_b32_e32 v45, 0
	v_mov_b32_e32 v46, 0
	v_mov_b32_e32 v47, 0
	v_mov_b32_e32 v48, 0
	v_mov_b32_e32 v49, 0
	v_mov_b32_e32 v50, 0
	v_mov_b32_e32 v51, 0
	v_mov_b32_e32 v52, 0
	v_mov_b32_e32 v53, 0
	v_mov_b32_e32 v58, 0
	v_mov_b32_e32 v59, 0
	v_mov_b32_e32 v60, 0
	v_mov_b32_e32 v61, 0
	v_mov_b32_e32 v62, 0
	v_mov_b32_e32 v63, 0
	v_mov_b32_e32 v64, 0
	v_mov_b32_e32 v65, 0
	v_mov_b32_e32 v66, 0
	v_mov_b32_e32 v67, 0
	v_mov_b32_e32 v68, 0
	v_mov_b32_e32 v69, 0
	v_mov_b32_e32 v70, 0
	v_mov_b32_e32 v71, 0
	v_mov_b32_e32 v72, 0
	v_mov_b32_e32 v73, 0
	v_mov_b32_e32 v78, 0
	v_mov_b32_e32 v79, 0
	v_mov_b32_e32 v80, 0
	v_mov_b32_e32 v81, 0
	v_mov_b32_e32 v82, 0
	v_mov_b32_e32 v83, 0
	v_mov_b32_e32 v84, 0
	v_mov_b32_e32 v85, 0
	v_mov_b32_e32 v86, 0
	v_mov_b32_e32 v87, 0
	v_mov_b32_e32 v88, 0
	v_mov_b32_e32 v89, 0
	v_mov_b32_e32 v94, 0
	v_mov_b32_e32 v95, 0
	v_mov_b32_e32 v96, 0
	v_mov_b32_e32 v97, 0
	v_mov_b32_e32 v98, 0
	v_mov_b32_e32 v99, 0
	v_mov_b32_e32 v100, 0
	v_mov_b32_e32 v101, 0
	v_mov_b32_e32 v102, 0
	v_mov_b32_e32 v103, 0
	v_mov_b32_e32 v104, 0
	v_mov_b32_e32 v105, 0
	v_mov_b32_e32 v110, 0
	v_mov_b32_e32 v111, 0
	v_mov_b32_e32 v112, 0
	v_mov_b32_e32 v113, 0
	s_and_saveexec_b64 s[2:3], vcc
	s_cbranch_execz .Lp1_ssq_done
	v_add_u32_e32 v12, s42, v154
	v_ashrrev_i32_e32 v13, 31, v12
	v_lshlrev_b64 v[12:13], 5, v[12:13]
	v_lshl_add_u64 v[16:17], s[24:25], 0, v[12:13]
	global_load_dwordx4 v[12:15], v[16:17], off
	s_nop 0
	global_load_dwordx4 v[16:19], v[16:17], off offset:16
	s_waitcnt vmcnt(1)
	v_mov_b32_e32 v20, v12
	s_waitcnt vmcnt(0)
	v_mov_b32_e32 v21, v16
	v_mov_b32_e32 v16, v13
	v_mov_b32_e32 v12, v14
	v_mov_b32_e32 v13, v18
	v_mov_b32_e32 v18, v15
	v_pk_add_f32 v[14:15], v[20:21], v[16:17]
	v_pk_add_f32 v[12:13], v[12:13], v[18:19]
	s_nop 0
	v_pk_add_f32 v[12:13], v[14:15], v[12:13]
	s_nop 0
	v_add_f32_e32 v12, v12, v13
	v_fmamk_f32 v12, v12, 0x3a800000, v231
	v_mul_f32_e32 v13, 0x4b800000, v12
	v_cmp_gt_f32_e64 s[16:17], s12, v12
	s_nop 1
	v_cndmask_b32_e64 v12, v12, v13, s[16:17]
	v_rsq_f32_e32 v12, v12
	s_nop 0
	v_mul_f32_e32 v13, 0x45800000, v12
	v_cndmask_b32_e64 v12, v12, v13, s[16:17]
	ds_write_b32 v160, v12

; #define WAIT_V(n) asm volatile("s_waitcnt vmcnt(" #n ")" ::: "memory")
; #define BAR __builtin_amdgcn_s_barrier()
; #define STAGEA(P, BASE, kt) do { const size_t SS_ = ssA; STAGE(P, BASE, kt); } while (0)
; #define STAGEB(P, BASE, kt) do { const size_t SS_ = ssB; STAGE(P, BASE, kt); } while (0)
; template <int EPI>
; __device__ void gemm8(const bf16* A, const bf16* Bt, const int K, const int ntN, const int ntTot, const EpiArgs ea, char* smem) {
;     ...
;     STAGEB(SB(0, 0), B0g, 0); STAGEA(SA(0, 0), A0, 0);
;     STAGEB(SB(0, 1), B1g, 0); STAGEA(SA(0, 1), A1, 0);
;     if (wr == 1) BAR;
;     WAIT_V(4); BAR;
;     STAGEB(SB(1, 0), B0g, 1); STAGEA(SA(1, 0), A0, 1); STAGEB(SB(1, 1), B1g, 1);
;     WAIT_V(6); BAR;
;     int a_rdo = a_rd, b_rdo = b_rd;
.LBB0_175:
	s_or_b64 exec, exec, s[2:3]
	s_mov_b64 s[2:3], 0x60000
	v_lshl_add_u64 v[4:5], v[2:3], 0, s[2:3]
	s_add_i32 s2, s23, 0x18000
	s_mov_b32 m0, s2
	s_mov_b64 s[16:17], 0x62000
	s_add_i32 s3, s23, 0x1a000
	s_waitcnt vmcnt(4)
	s_barrier
	global_load_lds_dwordx4 v[4:5], off
	v_lshl_add_u64 v[4:5], v[2:3], 0, s[16:17]
	s_mov_b32 m0, s3
	s_mov_b64 s[16:17], 0x200000
	s_add_i32 s46, s23, 0x8000
	global_load_lds_dwordx4 v[4:5], off
	v_lshl_add_u64 v[4:5], v[130:131], 0, s[16:17]
	s_mov_b32 m0, s46
	s_mov_b64 s[16:17], 0x202000
	s_add_i32 s47, s23, 0xa000
	global_load_lds_dwordx4 v[4:5], off
	v_lshl_add_u64 v[4:5], v[130:131], 0, s[16:17]
	s_mov_b32 m0, s47
	s_mov_b64 s[16:17], 0x64000
	s_add_i32 s48, s23, 0x1c000
	global_load_lds_dwordx4 v[4:5], off
	v_lshl_add_u64 v[4:5], v[2:3], 0, s[16:17]
	s_mov_b32 m0, s48
	s_mov_b64 s[16:17], 0x66000
	s_add_i32 s49, s23, 0x1e000
	global_load_lds_dwordx4 v[4:5], off
	v_lshl_add_u64 v[2:3], v[2:3], 0, s[16:17]
	s_mov_b32 m0, s49
	v_readlane_b32 s52, v253, 8
	global_load_lds_dwordx4 v[2:3], off
	s_waitcnt vmcnt(6)
	v_readlane_b32 s54, v253, 10
	v_readlane_b32 s55, v253, 11
	s_add_u32 s16, s54, s0
	v_mov_b32_e32 v2, 0
	s_addc_u32 s17, s55, s1
	s_mov_b32 s0, -2
	v_mov_b32_e32 v3, v2
	v_mov_b32_e32 v4, v2
	v_mov_b32_e32 v5, v2
	v_mov_b32_e32 v12, v2
	v_mov_b32_e32 v13, v2
	v_mov_b32_e32 v14, v2
	v_mov_b32_e32 v15, v2
	v_mov_b32_e32 v16, v2
	v_mov_b32_e32 v17, v2
	v_mov_b32_e32 v18, v2
	v_mov_b32_e32 v19, v2
	v_mov_b32_e32 v20, v2
	v_mov_b32_e32 v21, v2
	v_mov_b32_e32 v132, v158
	v_mov_b32_e32 v133, v159
	s_barrier
	v_readlane_b32 s53, v253, 9

; #define WAIT_V(n) asm volatile("s_waitcnt vmcnt(" #n ")" ::: "memory")
; #define BAR __builtin_amdgcn_s_barrier()
; #define STAGEA(P, BASE, kt) do { const size_t SS_ = ssA; STAGE(P, BASE, kt); } while (0)
; #define STAGEB(P, BASE, kt) do { const size_t SS_ = ssB; STAGE(P, BASE, kt); } while (0)
; template <int EPI>
; __device__ void gemm8(const bf16* A, const bf16* Bt, const int K, const int ntN, const int ntTot, const EpiArgs ea, char* smem) {
;     ...
;     f32x4 acc[2][2][4][2];
; #pragma unroll
;     for (int a = 0; a < 2; ++a)
; #pragma unroll
;       for (int b = 0; b < 2; ++b)
; #pragma unroll
;         for (int m = 0; m < 4; ++m)
; #pragma unroll
;           for (int n = 0; n < 2; ++n) acc[a][b][m][n] = f32x4{0.f, 0.f, 0.f, 0.f};
;     s16x8 At[4][2], B0[2][2], B1[2][2];
;     __syncthreads();
;     if (EPI != EPI_RES) {
;       if (tid < 256) {
;         const float* sq = ea.ssq + (size_t)(brow + tid) * 8;
;         const f32x4 q0 = *(const f32x4*)sq, q1 = *(const f32x4*)(sq + 4);
;         ssl[tid] = rsqrtf((((q0[0] + q0[1]) + (q0[2] + q0[3])) + ((q1[0] + q1[1]) + (q1[2] + q1[3]))) * (1.f / 1024.f) + EPS);
;       }
;     }
;     STAGEB(SB(0, 0), B0g, 0); STAGEA(SA(0, 0), A0, 0);
;     STAGEB(SB(0, 1), B1g, 0); STAGEA(SA(0, 1), A1, 0);
;     if (wr == 1) BAR;
;     WAIT_V(4); BAR;
.LBB0_797:
	s_ashr_i32 s0, s26, 31
	s_lshr_b32 s0, s0, 30
	s_add_i32 s0, s26, s0
	s_and_b32 s1, s0, -4
	s_lshl_b32 s0, s0, 6
	s_and_b32 s8, s0, 0xffffff00
	s_sub_i32 s6, s26, s1
	s_ashr_i32 s9, s8, 31
	s_lshl_b32 s4, s6, 8
	s_lshl_b64 s[0:1], s[8:9], 7
	v_readlane_b32 s2, v254, 58
	v_readlane_b32 s3, v254, 59
	s_add_u32 s10, s2, s0
	s_addc_u32 s11, s3, s1
	s_ashr_i32 s5, s4, 31
	s_lshl_b64 s[2:3], s[4:5], 7
	s_add_u32 s14, s13, s2
	s_addc_u32 s15, s20, s3
	s_add_i32 s5, s23, 0x10000
	v_lshl_add_u64 v[2:3], s[14:15], 0, v[186:187]
	s_mov_b32 m0, s5
	s_mov_b64 s[14:15], 0x2000
	s_add_i32 s7, s23, 0x12000
	s_barrier
	global_load_lds_dwordx4 v[2:3], off
	v_lshl_add_u64 v[4:5], v[2:3], 0, s[14:15]
	s_mov_b32 m0, s7
	v_lshl_add_u64 v[130:131], s[10:11], 0, v[186:187]
	global_load_lds_dwordx4 v[4:5], off
	s_mov_b32 m0, s23
	s_add_i32 s9, s23, 0x2000
	global_load_lds_dwordx4 v[130:131], off
	v_lshl_add_u64 v[4:5], v[130:131], 0, s[14:15]
	s_mov_b32 m0, s9
	s_mov_b64 s[10:11], 0x4000
	s_add_i32 s27, s23, 0x14000
	global_load_lds_dwordx4 v[4:5], off
	v_lshl_add_u64 v[4:5], v[2:3], 0, s[10:11]
	s_mov_b32 m0, s27
	s_mov_b64 s[14:15], 0x6000
	s_add_i32 s34, s23, 0x16000
	global_load_lds_dwordx4 v[4:5], off
	v_lshl_add_u64 v[4:5], v[2:3], 0, s[14:15]
	s_mov_b32 m0, s34
	s_add_i32 s35, s23, 0x4000
	global_load_lds_dwordx4 v[4:5], off
	v_lshl_add_u64 v[4:5], v[130:131], 0, s[10:11]
	s_mov_b32 m0, s35
	s_add_i32 s42, s23, 0x6000
	global_load_lds_dwordx4 v[4:5], off
	v_lshl_add_u64 v[4:5], v[130:131], 0, s[14:15]
	s_mov_b32 m0, s42
	s_nop 0
	global_load_lds_dwordx4 v[4:5], off
	v_mov_b32_e32 v6, 0
	v_mov_b32_e32 v7, 0
	v_mov_b32_e32 v8, 0
	v_mov_b32_e32 v9, 0
	v_mov_b32_e32 v10, 0
	v_mov_b32_e32 v11, 0
	v_mov_b32_e32 v12, 0
	v_mov_b32_e32 v13, 0
	v_mov_b32_e32 v14, 0
	v_mov_b32_e32 v15, 0
	v_mov_b32_e32 v16, 0
	v_mov_b32_e32 v17, 0
	v_mov_b32_e32 v18, 0
	v_mov_b32_e32 v19, 0
	v_mov_b32_e32 v20, 0
	v_mov_b32_e32 v21, 0
	v_mov_b32_e32 v22, 0
	v_mov_b32_e32 v23, 0
	v_mov_b32_e32 v24, 0
	v_mov_b32_e32 v25, 0
	v_mov_b32_e32 v26, 0
	v_mov_b32_e32 v27, 0
	v_mov_b32_e32 v28, 0
	v_mov_b32_e32 v29, 0
	v_mov_b32_e32 v30, 0
	v_mov_b32_e32 v31, 0
	v_mov_b32_e32 v32, 0
	v_mov_b32_e32 v33, 0
	v_mov_b32_e32 v54, 0
	v_mov_b32_e32 v55, 0
	v_mov_b32_e32 v56, 0
	v_mov_b32_e32 v57, 0
	v_mov_b32_e32 v74, 0
	v_mov_b32_e32 v75, 0
	v_mov_b32_e32 v76, 0
	v_mov_b32_e32 v77, 0
	v_mov_b32_e32 v90, 0
	v_mov_b32_e32 v91, 0
	v_mov_b32_e32 v92, 0
	v_mov_b32_e32 v93, 0
	v_mov_b32_e32 v106, 0
	v_mov_b32_e32 v107, 0
	v_mov_b32_e32 v108, 0
	v_mov_b32_e32 v109, 0
	v_mov_b32_e32 v114, 0
	v_mov_b32_e32 v115, 0
	v_mov_b32_e32 v116, 0
	v_mov_b32_e32 v117, 0
	v_mov_b32_e32 v118, 0
	v_mov_b32_e32 v119, 0
	v_mov_b32_e32 v120, 0
	v_mov_b32_e32 v121, 0
	v_mov_b32_e32 v122, 0
	v_mov_b32_e32 v123, 0
	v_mov_b32_e32 v124, 0
	v_mov_b32_e32 v125, 0
	v_mov_b32_e32 v126, 0
	v_mov_b32_e32 v127, 0
	v_mov_b32_e32 v128, 0
	v_mov_b32_e32 v129, 0
	v_mov_b32_e32 v34, 0
	v_mov_b32_e32 v35, 0
	v_mov_b32_e32 v36, 0
	v_mov_b32_e32 v37, 0
	v_mov_b32_e32 v38, 0
	v_mov_b32_e32 v39, 0
	v_mov_b32_e32 v40, 0
	v_mov_b32_e32 v41, 0
	v_mov_b32_e32 v42, 0
	v_mov_b32_e32 v43, 0
	v_mov_b32_e32 v44, 0
	v_mov_b32_e32 v45, 0
	v_mov_b32_e32 v46, 0
	v_mov_b32_e32 v47, 0
	v_mov_b32_e32 v48, 0
	v_mov_b32_e32 v49, 0
	v_mov_b32_e32 v50, 0
	v_mov_b32_e32 v51, 0
	v_mov_b32_e32 v52, 0
	v_mov_b32_e32 v53, 0
	v_mov_b32_e32 v58, 0
	v_mov_b32_e32 v59, 0
	v_mov_b32_e32 v60, 0
	v_mov_b32_e32 v61, 0
	v_mov_b32_e32 v62, 0
	v_mov_b32_e32 v63, 0
	v_mov_b32_e32 v64, 0
	v_mov_b32_e32 v65, 0
	v_mov_b32_e32 v66, 0
	v_mov_b32_e32 v67, 0
	v_mov_b32_e32 v68, 0
	v_mov_b32_e32 v69, 0
	v_mov_b32_e32 v70, 0
	v_mov_b32_e32 v71, 0
	v_mov_b32_e32 v72, 0
	v_mov_b32_e32 v73, 0
	v_mov_b32_e32 v78, 0
	v_mov_b32_e32 v79, 0
	v_mov_b32_e32 v80, 0
	v_mov_b32_e32 v81, 0
	v_mov_b32_e32 v82, 0
	v_mov_b32_e32 v83, 0
	v_mov_b32_e32 v84, 0
	v_mov_b32_e32 v85, 0
	v_mov_b32_e32 v86, 0
	v_mov_b32_e32 v87, 0
	v_mov_b32_e32 v88, 0
	v_mov_b32_e32 v89, 0
	v_mov_b32_e32 v94, 0
	v_mov_b32_e32 v95, 0
	v_mov_b32_e32 v96, 0
	v_mov_b32_e32 v97, 0
	v_mov_b32_e32 v98, 0
	v_mov_b32_e32 v99, 0
	v_mov_b32_e32 v100, 0
	v_mov_b32_e32 v101, 0
	v_mov_b32_e32 v102, 0
	v_mov_b32_e32 v103, 0
	v_mov_b32_e32 v104, 0
	v_mov_b32_e32 v105, 0
	v_mov_b32_e32 v110, 0
	v_mov_b32_e32 v111, 0
	v_mov_b32_e32 v112, 0
	v_mov_b32_e32 v113, 0
	s_and_saveexec_b64 s[10:11], vcc
	s_cbranch_execz .LBB0_799
	s_barrier
.LBB0_799:
	s_or_b64 exec, exec, s[10:11]
	s_add_i32 s10, s23, 0x18000
	v_lshl_add_u64 v[4:5], v[2:3], 0, s[28:29]
	s_mov_b32 m0, s10
	s_mov_b64 s[14:15], 0x22000
	s_add_i32 s11, s23, 0x1a000
	s_waitcnt vmcnt(4)
	s_barrier
	global_load_lds_dwordx4 v[4:5], off
	v_lshl_add_u64 v[4:5], v[2:3], 0, s[14:15]
	s_mov_b32 m0, s11
	s_mov_b64 s[14:15], 0x200000
	s_add_i32 s43, s23, 0x8000
	global_load_lds_dwordx4 v[4:5], off
	v_lshl_add_u64 v[4:5], v[130:131], 0, s[14:15]
	s_mov_b32 m0, s43
	s_mov_b64 s[14:15], 0x202000
	s_add_i32 s44, s23, 0xa000
	global_load_lds_dwordx4 v[4:5], off
	v_lshl_add_u64 v[4:5], v[130:131], 0, s[14:15]
	s_mov_b32 m0, s44
	s_mov_b64 s[14:15], 0x24000
	s_add_i32 s45, s23, 0x1c000
	global_load_lds_dwordx4 v[4:5], off
	v_lshl_add_u64 v[4:5], v[2:3], 0, s[14:15]
	s_mov_b32 m0, s45
	s_mov_b64 s[14:15], 0x26000
	s_add_i32 s46, s23, 0x1e000
	global_load_lds_dwordx4 v[4:5], off
	v_lshl_add_u64 v[2:3], v[2:3], 0, s[14:15]
	s_mov_b32 m0, s46
	v_readlane_b32 s48, v253, 8
	global_load_lds_dwordx4 v[2:3], off
	v_readlane_b32 s50, v253, 10
	v_readlane_b32 s51, v253, 11
	s_add_u32 s14, s50, s0
	s_waitcnt vmcnt(6)
	s_addc_u32 s15, s51, s1
	s_add_u32 s16, s21, s2
	v_mov_b32_e32 v2, 0
	s_addc_u32 s17, s22, s3
	s_mov_b32 s0, -2
	v_mov_b32_e32 v0, v207
	v_mov_b32_e32 v132, v209
	v_mov_b32_e32 v3, v2
	v_mov_b32_e32 v4, v2
	v_mov_b32_e32 v5, v2
	s_barrier
	v_readlane_b32 s49, v253, 9

; #define STAGEA(P, BASE, kt) do { const size_t SS_ = ssA; STAGE(P, BASE, kt); } while (0)
; #define STAGEB(P, BASE, kt) do { const size_t SS_ = ssB; STAGE(P, BASE, kt); } while (0)
; template <int EPI>
; __device__ void gemm8(const bf16* A, const bf16* Bt, const int K, const int ntN, const int ntTot, const EpiArgs ea, char* smem) {
;     ...
;     f32x4 acc[2][2][4][2];
; #pragma unroll
;     for (int a = 0; a < 2; ++a)
; #pragma unroll
;       for (int b = 0; b < 2; ++b)
; #pragma unroll
;         for (int m = 0; m < 4; ++m)
; #pragma unroll
;           for (int n = 0; n < 2; ++n) acc[a][b][m][n] = f32x4{0.f, 0.f, 0.f, 0.f};
;     s16x8 At[4][2], B0[2][2], B1[2][2];
;     __syncthreads();
;     if (EPI != EPI_RES) {
;       if (tid < 256) {
;         const float* sq = ea.ssq + (size_t)(brow + tid) * 8;
;         const f32x4 q0 = *(const f32x4*)sq, q1 = *(const f32x4*)(sq + 4);
;         ssl[tid] = rsqrtf((((q0[0] + q0[1]) + (q0[2] + q0[3])) + ((q1[0] + q1[1]) + (q1[2] + q1[3]))) * (1.f / 1024.f) + EPS);
;       }
;     }
;     STAGEB(SB(0, 0), B0g, 0); STAGEA(SA(0, 0), A0, 0);
;     STAGEB(SB(0, 1), B1g, 0); STAGEA(SA(0, 1), A1, 0);
.LBB0_877:
	s_ashr_i32 s0, s26, 31
	s_lshr_b32 s0, s0, 28
	s_add_i32 s0, s26, s0
	s_ashr_i32 s2, s0, 4
	s_lshl_b32 s4, s2, 8
	s_barrier
	s_lshl_b32 s0, s2, 4
	s_sub_i32 s0, s26, s0
	s_ashr_i32 s5, s4, 31
	s_lshl_b32 s8, s0, 8
	s_lshl_b64 s[0:1], s[4:5], 7
	s_add_u32 s10, s18, s0
	s_addc_u32 s11, s19, s1
	s_ashr_i32 s9, s8, 31
	s_lshl_b64 s[2:3], s[8:9], 7
	s_add_u32 s14, s13, s2
	s_addc_u32 s15, s20, s3
	s_add_i32 s5, s23, 0x10000
	v_lshl_add_u64 v[2:3], s[14:15], 0, v[0:1]
	s_mov_b32 m0, s5
	s_mov_b64 s[14:15], 0x2000
	s_add_i32 s9, s23, 0x12000
	global_load_lds_dwordx4 v[2:3], off
	v_lshl_add_u64 v[4:5], v[2:3], 0, s[14:15]
	s_mov_b32 m0, s9
	v_lshl_add_u64 v[134:135], s[10:11], 0, v[0:1]
	global_load_lds_dwordx4 v[4:5], off
	s_mov_b32 m0, s23
	s_add_i32 s27, s23, 0x2000
	global_load_lds_dwordx4 v[134:135], off
	v_lshl_add_u64 v[4:5], v[134:135], 0, s[14:15]
	s_mov_b32 m0, s27
	s_mov_b64 s[10:11], 0x4000
	s_add_i32 s34, s23, 0x14000
	global_load_lds_dwordx4 v[4:5], off
	v_lshl_add_u64 v[4:5], v[2:3], 0, s[10:11]
	s_mov_b32 m0, s34
	s_mov_b64 s[14:15], 0x6000
	s_add_i32 s35, s23, 0x16000
	global_load_lds_dwordx4 v[4:5], off
	v_lshl_add_u64 v[4:5], v[2:3], 0, s[14:15]
	s_mov_b32 m0, s35
	s_add_i32 s42, s23, 0x4000
	global_load_lds_dwordx4 v[4:5], off
	v_lshl_add_u64 v[4:5], v[134:135], 0, s[10:11]
	s_mov_b32 m0, s42
	s_add_i32 s43, s23, 0x6000
	global_load_lds_dwordx4 v[4:5], off
	v_lshl_add_u64 v[4:5], v[134:135], 0, s[14:15]
	s_mov_b32 m0, s43
	s_nop 0
	global_load_lds_dwordx4 v[4:5], off
	v_mov_b32_e32 v6, 0
	v_mov_b32_e32 v7, 0
	v_mov_b32_e32 v8, 0
	v_mov_b32_e32 v9, 0
	v_mov_b32_e32 v10, 0
	v_mov_b32_e32 v11, 0
	v_mov_b32_e32 v22, 0
	v_mov_b32_e32 v23, 0
	v_mov_b32_e32 v24, 0
	v_mov_b32_e32 v25, 0
	v_mov_b32_e32 v26, 0
	v_mov_b32_e32 v27, 0
	v_mov_b32_e32 v28, 0
	v_mov_b32_e32 v29, 0
	v_mov_b32_e32 v30, 0
	v_mov_b32_e32 v31, 0
	v_mov_b32_e32 v32, 0
	v_mov_b32_e32 v33, 0
	v_mov_b32_e32 v34, 0
	v_mov_b32_e32 v35, 0
	v_mov_b32_e32 v36, 0
	v_mov_b32_e32 v37, 0
	v_mov_b32_e32 v38, 0
	v_mov_b32_e32 v39, 0
	v_mov_b32_e32 v40, 0
	v_mov_b32_e32 v41, 0
	v_mov_b32_e32 v42, 0
	v_mov_b32_e32 v43, 0
	v_mov_b32_e32 v44, 0
	v_mov_b32_e32 v45, 0
	v_mov_b32_e32 v46, 0
	v_mov_b32_e32 v47, 0
	v_mov_b32_e32 v48, 0
	v_mov_b32_e32 v49, 0
	v_mov_b32_e32 v50, 0
	v_mov_b32_e32 v51, 0
	v_mov_b32_e32 v52, 0
	v_mov_b32_e32 v53, 0
	v_mov_b32_e32 v54, 0
	v_mov_b32_e32 v55, 0
	v_mov_b32_e32 v56, 0
	v_mov_b32_e32 v57, 0
	v_mov_b32_e32 v58, 0
	v_mov_b32_e32 v59, 0
	v_mov_b32_e32 v60, 0
	v_mov_b32_e32 v61, 0
	v_mov_b32_e32 v62, 0
	v_mov_b32_e32 v63, 0
	v_mov_b32_e32 v64, 0
	v_mov_b32_e32 v65, 0
	v_mov_b32_e32 v66, 0
	v_mov_b32_e32 v67, 0
	v_mov_b32_e32 v68, 0
	v_mov_b32_e32 v69, 0
	v_mov_b32_e32 v70, 0
	v_mov_b32_e32 v71, 0
	v_mov_b32_e32 v72, 0
	v_mov_b32_e32 v73, 0
	v_mov_b32_e32 v74, 0
	v_mov_b32_e32 v75, 0
	v_mov_b32_e32 v76, 0
	v_mov_b32_e32 v77, 0
	v_mov_b32_e32 v78, 0
	v_mov_b32_e32 v79, 0
	v_mov_b32_e32 v80, 0
	v_mov_b32_e32 v81, 0
	v_mov_b32_e32 v82, 0
	v_mov_b32_e32 v83, 0
	v_mov_b32_e32 v84, 0
	v_mov_b32_e32 v85, 0
	v_mov_b32_e32 v86, 0
	v_mov_b32_e32 v87, 0
	v_mov_b32_e32 v88, 0
	v_mov_b32_e32 v89, 0
	v_mov_b32_e32 v90, 0
	v_mov_b32_e32 v91, 0
	v_mov_b32_e32 v92, 0
	v_mov_b32_e32 v93, 0
	v_mov_b32_e32 v94, 0
	v_mov_b32_e32 v95, 0
	v_mov_b32_e32 v96, 0
	v_mov_b32_e32 v97, 0
	v_mov_b32_e32 v98, 0
	v_mov_b32_e32 v99, 0
	v_mov_b32_e32 v100, 0
	v_mov_b32_e32 v101, 0
	v_mov_b32_e32 v102, 0
	v_mov_b32_e32 v103, 0
	v_mov_b32_e32 v104, 0
	v_mov_b32_e32 v105, 0
	v_mov_b32_e32 v106, 0
	v_mov_b32_e32 v107, 0
	v_mov_b32_e32 v108, 0
	v_mov_b32_e32 v109, 0
	v_mov_b32_e32 v110, 0
	v_mov_b32_e32 v111, 0
	v_mov_b32_e32 v112, 0
	v_mov_b32_e32 v113, 0
	v_mov_b32_e32 v114, 0
	v_mov_b32_e32 v115, 0
	v_mov_b32_e32 v116, 0
	v_mov_b32_e32 v117, 0
	v_mov_b32_e32 v118, 0
	v_mov_b32_e32 v119, 0
	v_mov_b32_e32 v120, 0
	v_mov_b32_e32 v121, 0
	v_mov_b32_e32 v122, 0
	v_mov_b32_e32 v123, 0
	v_mov_b32_e32 v124, 0
	v_mov_b32_e32 v125, 0
	v_mov_b32_e32 v126, 0
	v_mov_b32_e32 v127, 0
	v_mov_b32_e32 v128, 0
	v_mov_b32_e32 v129, 0
	s_and_saveexec_b64 s[10:11], s[36:37]
	s_cbranch_execz .Lp3b_ssq_done
	v_add_u32_e32 v12, s4, v138
	v_ashrrev_i32_e32 v13, 31, v12
	v_lshlrev_b64 v[12:13], 5, v[12:13]
	v_lshl_add_u64 v[16:17], s[24:25], 0, v[12:13]
	global_load_dwordx4 v[12:15], v[16:17], off
	s_nop 0
	global_load_dwordx4 v[16:19], v[16:17], off offset:16
	s_waitcnt vmcnt(0)
	v_mov_b32_e32 v20, v12
	s_waitcnt vmcnt(0)
	v_mov_b32_e32 v21, v16
	v_mov_b32_e32 v16, v13
	v_mov_b32_e32 v12, v14
	v_mov_b32_e32 v13, v18
	v_mov_b32_e32 v18, v15
	v_pk_add_f32 v[14:15], v[20:21], v[16:17]
	v_pk_add_f32 v[12:13], v[12:13], v[18:19]
	s_nop 0
	v_pk_add_f32 v[12:13], v[14:15], v[12:13]
	s_nop 0
	v_add_f32_e32 v12, v12, v13
	v_fmamk_f32 v12, v12, 0x3a800000, v231
	v_mul_f32_e32 v13, 0x4b800000, v12
	v_cmp_gt_f32_e32 vcc, s12, v12
	s_nop 1
	v_cndmask_b32_e32 v12, v12, v13, vcc
	v_rsq_f32_e32 v12, v12
	s_nop 0
	v_mul_f32_e32 v13, 0x45800000, v12
	v_cndmask_b32_e32 v12, v12, v13, vcc
	ds_write_b32 v143, v12

; #define WAIT_V(n) asm volatile("s_waitcnt vmcnt(" #n ")" ::: "memory")
; #define BAR __builtin_amdgcn_s_barrier()
; #define STAGEA(P, BASE, kt) do { const size_t SS_ = ssA; STAGE(P, BASE, kt); } while (0)
; #define STAGEB(P, BASE, kt) do { const size_t SS_ = ssB; STAGE(P, BASE, kt); } while (0)
; template <int EPI>
; __device__ void gemm8(const bf16* A, const bf16* Bt, const int K, const int ntN, const int ntTot, const EpiArgs ea, char* smem) {
;     ...
;     STAGEB(SB(0, 0), B0g, 0); STAGEA(SA(0, 0), A0, 0);
;     STAGEB(SB(0, 1), B1g, 0); STAGEA(SA(0, 1), A1, 0);
;     if (wr == 1) BAR;
;     WAIT_V(4); BAR;
;     STAGEB(SB(1, 0), B0g, 1); STAGEA(SA(1, 0), A0, 1); STAGEB(SB(1, 1), B1g, 1);
;     WAIT_V(6); BAR;
;     int a_rdo = a_rd, b_rdo = b_rd;
.LBB0_881:
	s_or_b64 exec, exec, s[10:11]
	s_mov_b64 s[10:11], 0x80000
	v_lshl_add_u64 v[4:5], v[2:3], 0, s[10:11]
	s_add_i32 s10, s23, 0x18000
	s_mov_b32 m0, s10
	s_mov_b64 s[14:15], 0x82000
	s_add_i32 s11, s23, 0x1a000
	s_waitcnt vmcnt(4)
	s_barrier
	global_load_lds_dwordx4 v[4:5], off
	v_lshl_add_u64 v[4:5], v[2:3], 0, s[14:15]
	s_mov_b32 m0, s11
	s_mov_b64 s[14:15], 0x200000
	s_add_i32 s44, s23, 0x8000
	global_load_lds_dwordx4 v[4:5], off
	v_lshl_add_u64 v[4:5], v[134:135], 0, s[14:15]
	s_mov_b32 m0, s44
	s_mov_b64 s[14:15], 0x202000
	s_add_i32 s45, s23, 0xa000
	global_load_lds_dwordx4 v[4:5], off
	v_lshl_add_u64 v[4:5], v[134:135], 0, s[14:15]
	s_mov_b32 m0, s45
	s_mov_b64 s[14:15], 0x84000
	s_add_i32 s46, s23, 0x1c000
	global_load_lds_dwordx4 v[4:5], off
	v_lshl_add_u64 v[4:5], v[2:3], 0, s[14:15]
	s_mov_b32 m0, s46
	s_mov_b64 s[14:15], 0x86000
	s_add_i32 s47, s23, 0x1e000
	global_load_lds_dwordx4 v[4:5], off
	v_lshl_add_u64 v[2:3], v[2:3], 0, s[14:15]
	s_mov_b32 m0, s47
	v_readlane_b32 s48, v253, 8
	global_load_lds_dwordx4 v[2:3], off
	v_readlane_b32 s50, v253, 10
	v_readlane_b32 s51, v253, 11
	s_add_u32 s14, s50, s0
	s_waitcnt vmcnt(6)
	s_addc_u32 s15, s51, s1
	s_add_u32 s16, s21, s2
	v_mov_b32_e32 v2, 0
	s_addc_u32 s17, s22, s3
	s_mov_b32 s0, -2
	v_mov_b32_e32 v136, v140
	v_mov_b32_e32 v137, v142
	v_mov_b32_e32 v3, v2
	v_mov_b32_e32 v4, v2
	v_mov_b32_e32 v5, v2
	v_mov_b32_e32 v12, v2
	v_mov_b32_e32 v13, v2
	v_mov_b32_e32 v14, v2
	v_mov_b32_e32 v15, v2
	v_mov_b32_e32 v16, v2
	v_mov_b32_e32 v17, v2
	v_mov_b32_e32 v18, v2
	v_mov_b32_e32 v19, v2
	v_mov_b32_e32 v20, v2
	v_mov_b32_e32 v21, v2
	s_barrier
	v_readlane_b32 s49, v253, 9

; #define WAIT_V(n) asm volatile("s_waitcnt vmcnt(" #n ")" ::: "memory")
; #define BAR __builtin_amdgcn_s_barrier()
; #define STAGEA(P, BASE, kt) do { const size_t SS_ = ssA; STAGE(P, BASE, kt); } while (0)
; #define STAGEB(P, BASE, kt) do { const size_t SS_ = ssB; STAGE(P, BASE, kt); } while (0)
; template <int EPI>
; __device__ void gemm8(const bf16* A, const bf16* Bt, const int K, const int ntN, const int ntTot, const EpiArgs ea, char* smem) {
;     ...
;     f32x4 acc[2][2][4][2];
; #pragma unroll
;     for (int a = 0; a < 2; ++a)
; #pragma unroll
;       for (int b = 0; b < 2; ++b)
; #pragma unroll
;         for (int m = 0; m < 4; ++m)
; #pragma unroll
;           for (int n = 0; n < 2; ++n) acc[a][b][m][n] = f32x4{0.f, 0.f, 0.f, 0.f};
;     s16x8 At[4][2], B0[2][2], B1[2][2];
;     __syncthreads();
;     if (EPI != EPI_RES) {
;       if (tid < 256) {
;         const float* sq = ea.ssq + (size_t)(brow + tid) * 8;
;         const f32x4 q0 = *(const f32x4*)sq, q1 = *(const f32x4*)(sq + 4);
;         ssl[tid] = rsqrtf((((q0[0] + q0[1]) + (q0[2] + q0[3])) + ((q1[0] + q1[1]) + (q1[2] + q1[3]))) * (1.f / 1024.f) + EPS);
;       }
;     }
;     STAGEB(SB(0, 0), B0g, 0); STAGEA(SA(0, 0), A0, 0);
;     STAGEB(SB(0, 1), B1g, 0); STAGEA(SA(0, 1), A1, 0);
;     if (wr == 1) BAR;
;     WAIT_V(4); BAR;
.LBB0_941:
	s_ashr_i32 s0, s34, 31
	s_lshr_b32 s0, s0, 30
	s_add_i32 s0, s34, s0
	s_and_b32 s1, s0, -4
	s_lshl_b32 s0, s0, 6
	s_and_b32 s8, s0, 0xffffff00
	s_sub_i32 s6, s34, s1
	s_ashr_i32 s9, s8, 31
	s_lshl_b32 s14, s6, 8
	s_lshl_b64 s[0:1], s[8:9], 7
	v_readlane_b32 s2, v254, 42
	v_readlane_b32 s3, v254, 43
	s_add_u32 s10, s2, s0
	s_addc_u32 s11, s3, s1
	s_ashr_i32 s15, s14, 31
	s_lshl_b64 s[2:3], s[14:15], 7
	s_add_u32 s16, s13, s2
	s_addc_u32 s17, s22, s3
	s_add_i32 s7, s27, 0x10000
	v_lshl_add_u64 v[2:3], s[16:17], 0, v[192:193]
	s_mov_b32 m0, s7
	s_mov_b64 s[16:17], 0x2000
	s_add_i32 s9, s27, 0x12000
	s_barrier
	global_load_lds_dwordx4 v[2:3], off
	v_lshl_add_u64 v[4:5], v[2:3], 0, s[16:17]
	s_mov_b32 m0, s9
	v_lshl_add_u64 v[130:131], s[10:11], 0, v[192:193]
	global_load_lds_dwordx4 v[4:5], off
	s_mov_b32 m0, s27
	s_add_i32 s15, s27, 0x2000
	global_load_lds_dwordx4 v[130:131], off
	v_lshl_add_u64 v[4:5], v[130:131], 0, s[16:17]
	s_mov_b32 m0, s15
	s_mov_b64 s[10:11], 0x4000
	s_add_i32 s35, s27, 0x14000
	global_load_lds_dwordx4 v[4:5], off
	v_lshl_add_u64 v[4:5], v[2:3], 0, s[10:11]
	s_mov_b32 m0, s35
	s_mov_b64 s[16:17], 0x6000
	s_add_i32 s44, s27, 0x16000
	global_load_lds_dwordx4 v[4:5], off
	v_lshl_add_u64 v[4:5], v[2:3], 0, s[16:17]
	s_mov_b32 m0, s44
	s_add_i32 s45, s27, 0x4000
	global_load_lds_dwordx4 v[4:5], off
	v_lshl_add_u64 v[4:5], v[130:131], 0, s[10:11]
	s_mov_b32 m0, s45
	s_add_i32 s46, s27, 0x6000
	global_load_lds_dwordx4 v[4:5], off
	v_lshl_add_u64 v[4:5], v[130:131], 0, s[16:17]
	s_mov_b32 m0, s46
	s_nop 0
	global_load_lds_dwordx4 v[4:5], off
	v_mov_b32_e32 v6, 0
	v_mov_b32_e32 v7, 0
	v_mov_b32_e32 v8, 0
	v_mov_b32_e32 v9, 0
	v_mov_b32_e32 v10, 0
	v_mov_b32_e32 v11, 0
	v_mov_b32_e32 v12, 0
	v_mov_b32_e32 v13, 0
	v_mov_b32_e32 v14, 0
	v_mov_b32_e32 v15, 0
	v_mov_b32_e32 v16, 0
	v_mov_b32_e32 v17, 0
	v_mov_b32_e32 v18, 0
	v_mov_b32_e32 v19, 0
	v_mov_b32_e32 v20, 0
	v_mov_b32_e32 v21, 0
	v_mov_b32_e32 v22, 0
	v_mov_b32_e32 v23, 0
	v_mov_b32_e32 v24, 0
	v_mov_b32_e32 v25, 0
	v_mov_b32_e32 v26, 0
	v_mov_b32_e32 v27, 0
	v_mov_b32_e32 v28, 0
	v_mov_b32_e32 v29, 0
	v_mov_b32_e32 v30, 0
	v_mov_b32_e32 v31, 0
	v_mov_b32_e32 v32, 0
	v_mov_b32_e32 v33, 0
	v_mov_b32_e32 v54, 0
	v_mov_b32_e32 v55, 0
	v_mov_b32_e32 v56, 0
	v_mov_b32_e32 v57, 0
	v_mov_b32_e32 v74, 0
	v_mov_b32_e32 v75, 0
	v_mov_b32_e32 v76, 0
	v_mov_b32_e32 v77, 0
	v_mov_b32_e32 v90, 0
	v_mov_b32_e32 v91, 0
	v_mov_b32_e32 v92, 0
	v_mov_b32_e32 v93, 0
	v_mov_b32_e32 v106, 0
	v_mov_b32_e32 v107, 0
	v_mov_b32_e32 v108, 0
	v_mov_b32_e32 v109, 0
	v_mov_b32_e32 v114, 0
	v_mov_b32_e32 v115, 0
	v_mov_b32_e32 v116, 0
	v_mov_b32_e32 v117, 0
	v_mov_b32_e32 v118, 0
	v_mov_b32_e32 v119, 0
	v_mov_b32_e32 v120, 0
	v_mov_b32_e32 v121, 0
	v_mov_b32_e32 v122, 0
	v_mov_b32_e32 v123, 0
	v_mov_b32_e32 v124, 0
	v_mov_b32_e32 v125, 0
	v_mov_b32_e32 v126, 0
	v_mov_b32_e32 v127, 0
	v_mov_b32_e32 v128, 0
	v_mov_b32_e32 v129, 0
	v_mov_b32_e32 v34, 0
	v_mov_b32_e32 v35, 0
	v_mov_b32_e32 v36, 0
	v_mov_b32_e32 v37, 0
	v_mov_b32_e32 v38, 0
	v_mov_b32_e32 v39, 0
	v_mov_b32_e32 v40, 0
	v_mov_b32_e32 v41, 0
	v_mov_b32_e32 v42, 0
	v_mov_b32_e32 v43, 0
	v_mov_b32_e32 v44, 0
	v_mov_b32_e32 v45, 0
	v_mov_b32_e32 v46, 0
	v_mov_b32_e32 v47, 0
	v_mov_b32_e32 v48, 0
	v_mov_b32_e32 v49, 0
	v_mov_b32_e32 v50, 0
	v_mov_b32_e32 v51, 0
	v_mov_b32_e32 v52, 0
	v_mov_b32_e32 v53, 0
	v_mov_b32_e32 v58, 0
	v_mov_b32_e32 v59, 0
	v_mov_b32_e32 v60, 0
	v_mov_b32_e32 v61, 0
	v_mov_b32_e32 v62, 0
	v_mov_b32_e32 v63, 0
	v_mov_b32_e32 v64, 0
	v_mov_b32_e32 v65, 0
	v_mov_b32_e32 v66, 0
	v_mov_b32_e32 v67, 0
	v_mov_b32_e32 v68, 0
	v_mov_b32_e32 v69, 0
	v_mov_b32_e32 v70, 0
	v_mov_b32_e32 v71, 0
	v_mov_b32_e32 v72, 0
	v_mov_b32_e32 v73, 0
	v_mov_b32_e32 v78, 0
	v_mov_b32_e32 v79, 0
	v_mov_b32_e32 v80, 0
	v_mov_b32_e32 v81, 0
	v_mov_b32_e32 v82, 0
	v_mov_b32_e32 v83, 0
	v_mov_b32_e32 v84, 0
	v_mov_b32_e32 v85, 0
	v_mov_b32_e32 v86, 0
	v_mov_b32_e32 v87, 0
	v_mov_b32_e32 v88, 0
	v_mov_b32_e32 v89, 0
	v_mov_b32_e32 v94, 0
	v_mov_b32_e32 v95, 0
	v_mov_b32_e32 v96, 0
	v_mov_b32_e32 v97, 0
	v_mov_b32_e32 v98, 0
	v_mov_b32_e32 v99, 0
	v_mov_b32_e32 v100, 0
	v_mov_b32_e32 v101, 0
	v_mov_b32_e32 v102, 0
	v_mov_b32_e32 v103, 0
	v_mov_b32_e32 v104, 0
	v_mov_b32_e32 v105, 0
	v_mov_b32_e32 v110, 0
	v_mov_b32_e32 v111, 0
	v_mov_b32_e32 v112, 0
	v_mov_b32_e32 v113, 0
	s_and_saveexec_b64 s[10:11], s[36:37]
	s_cbranch_execz .LBB0_943
	s_barrier
.LBB0_943:
	s_or_b64 exec, exec, s[10:11]
	s_add_i32 s10, s27, 0x18000
	v_lshl_add_u64 v[4:5], v[2:3], 0, s[28:29]
	s_mov_b32 m0, s10
	s_mov_b64 s[16:17], 0x22000
	s_add_i32 s11, s27, 0x1a000
	s_waitcnt vmcnt(4)
	s_barrier
	global_load_lds_dwordx4 v[4:5], off
	v_lshl_add_u64 v[4:5], v[2:3], 0, s[16:17]
	s_mov_b32 m0, s11
	s_mov_b64 s[16:17], 0x200000
	s_add_i32 s47, s27, 0x8000
	global_load_lds_dwordx4 v[4:5], off
	v_lshl_add_u64 v[4:5], v[130:131], 0, s[16:17]
	s_mov_b32 m0, s47
	s_mov_b64 s[16:17], 0x202000
	s_add_i32 s48, s27, 0xa000
	global_load_lds_dwordx4 v[4:5], off
	v_lshl_add_u64 v[4:5], v[130:131], 0, s[16:17]
	s_mov_b32 m0, s48
	s_mov_b64 s[16:17], 0x24000
	s_add_i32 s49, s27, 0x1c000
	global_load_lds_dwordx4 v[4:5], off
	v_lshl_add_u64 v[4:5], v[2:3], 0, s[16:17]
	s_mov_b32 m0, s49
	s_mov_b64 s[16:17], 0x26000
	s_add_i32 s50, s27, 0x1e000
	global_load_lds_dwordx4 v[4:5], off
	v_lshl_add_u64 v[2:3], v[2:3], 0, s[16:17]
	s_mov_b32 m0, s50
	v_readlane_b32 s52, v253, 8
	global_load_lds_dwordx4 v[2:3], off
	v_readlane_b32 s54, v253, 10
	v_readlane_b32 s55, v253, 11
	s_add_u32 s16, s54, s0
	s_waitcnt vmcnt(6)
	s_addc_u32 s17, s55, s1
	s_add_u32 s20, s23, s2
	v_mov_b32_e32 v2, 0
	s_addc_u32 s21, s26, s3
	s_mov_b32 s0, -2
	v_mov_b32_e32 v0, v239
	v_mov_b32_e32 v132, v241
	v_mov_b32_e32 v3, v2
	v_mov_b32_e32 v4, v2
	v_mov_b32_e32 v5, v2
	s_barrier
	v_readlane_b32 s53, v253, 9
